# P3 q-up unit ranges re-dealt so no workgroup gets more than two rotary (serialised-epilogue) tiles; on top of v54
# speedup vs baseline: 1.0035x; 1.0035x over previous
; #define LAS __attribute__((address_space(3)))
; __global__ void __launch_bounds__(512, 2) fwd(Args args) {
;     ...
;         const int nq = (int)((0x0304040404020201ull >> (8 * m8)) & 0xff), pq = (int)((0x15110d0905030100ull >> (8 * m8)) & 0xff);
;         const int nkv = (int)((0x0504040404040403ull >> (8 * m8)) & 0xff), pkv = (int)((0x1b17130f0b070300ull >> (8 * m8)) & 0xff);
;         LAS float* rfq = (LAS float*)(F.lds + RING_BYTES + 4096); LAS float* rfkv = rfq + 512;
;         {   const int row = 512 * a8 + F.tid;
;             const f32x4* pq4 = (const f32x4*)((const float*)(ws + WS_RSSQ) + (size_t)row * 24); f32x4 sq = pq4[0];
; #pragma unroll
;             for (int i = 1; i < 6; ++i) sq += pq4[i];
;             const f32x4* pk4 = (const f32x4*)((const float*)(ws + WS_RSSKV) + (size_t)row * 8); const f32x4 sk = pk4[0] + pk4[1];
;             rfq[F.tid] = 1.0f / sqrtf(((sq[0] + sq[1]) + (sq[2] + sq[3])) * (1.0f / QR) + 1e-6f);
;             rfkv[F.tid] = 1.0f / sqrtf(((sk[0] + sk[1]) + (sk[2] + sk[3])) * (1.0f / KVR) + 1e-6f);
;             __syncthreads(); }
;         {
;             pg8::GLin g{(const bf16_t*)(ws + WS_CQ), (const bf16_t*)(ws + WS_WUQT), FP8_UP ? QR * 1u : QR * 2u, FP8_UP ? QR * 1u : QR * 2u, FP8_UP ? QR / 2 : QR}; pg8::RangeOrder So{24 * a8 + pq, nq, 12};
.LBB0_710:
	s_lshl_b32 s62, s50, 9
	v_or_b32_e32 v18, s62, v0
	s_movk_i32 s0, 0x60
	v_mov_b64_e32 v[2:3], s[30:31]
	v_mad_i64_i32 v[2:3], s[0:1], v18, s0, v[2:3]
	s_mov_b64 s[0:1], 0x2df00000
	s_nop 0
	v_lshl_add_u64 v[34:35], v[2:3], 0, s[0:1]
	s_mov_b32 s0, 0x2df00000
	v_ashrrev_i32_e32 v19, 31, v18
	v_add_co_u32_e32 v20, vcc, s0, v2
	v_lshlrev_b64 v[18:19], 5, v[18:19]
	s_nop 0
	v_addc_co_u32_e32 v21, vcc, 0, v3, vcc
	global_load_dwordx4 v[2:5], v[20:21], off
	global_load_dwordx4 v[6:9], v[34:35], off offset:48
	global_load_dwordx4 v[10:13], v[34:35], off offset:32
	global_load_dwordx4 v[14:17], v[34:35], off offset:16
	v_lshl_add_u64 v[18:19], s[30:31], 0, v[18:19]
	s_mov_b64 s[0:1], 0x2e100000
	v_lshl_add_u64 v[36:37], v[18:19], 0, s[0:1]
	s_mov_b32 s0, 0x2e100000
	v_add_co_u32_e32 v38, vcc, s0, v18
	s_mov_b32 s0, 0x4020201
	s_nop 0
	v_addc_co_u32_e32 v39, vcc, 0, v19, vcc
	global_load_dwordx4 v[18:21], v[38:39], off
	global_load_dwordx4 v[22:25], v[36:37], off offset:16
	global_load_dwordx4 v[26:29], v[34:35], off offset:64
	global_load_dwordx4 v[30:33], v[34:35], off offset:80
	v_mov_b32_e32 v34, 0x358637bd
	s_lshl_b32 s33, s33, 3
	s_mov_b32 s1, 0x3040404
	s_mov_b32 s8, 0xf800000
	s_lshr_b64 s[0:1], s[0:1], s33
	s_and_b32 s44, s0, 7
	s_mov_b32 s2, 0x160812
	s_mov_b32 s3, 0x130e0a04
	s_lshr_b64 s[2:3], s[2:3], s33
	s_and_b32 s45, s2, 31
	v_mov_b32_e32 v35, 0x260
	v_add_u32_e32 v36, 0x21000, v178
	v_readfirstlane_b32 s28, v0
	s_waitcnt vmcnt(0)
	v_pk_add_f32 v[4:5], v[4:5], v[16:17]
	v_pk_add_f32 v[2:3], v[2:3], v[14:15]
	v_pk_add_f32 v[4:5], v[4:5], v[12:13]
	v_pk_add_f32 v[2:3], v[2:3], v[10:11]
	v_pk_add_f32 v[4:5], v[4:5], v[8:9]
	v_pk_add_f32 v[2:3], v[2:3], v[6:7]
	v_pk_add_f32 v[6:7], v[20:21], v[24:25]
	v_pk_add_f32 v[4:5], v[4:5], v[28:29]
	v_pk_add_f32 v[2:3], v[2:3], v[26:27]
	v_pk_add_f32 v[4:5], v[4:5], v[32:33]
	v_pk_add_f32 v[2:3], v[2:3], v[30:31]
	v_pk_add_f32 v[8:9], v[18:19], v[22:23]
	v_add_f32_e32 v2, v2, v3
	v_add_f32_e32 v3, v4, v5
	v_add_f32_e32 v8, v8, v9
	v_add_f32_e32 v6, v6, v7
	v_add_f32_e32 v2, v2, v3
	v_add_f32_e32 v6, v8, v6
	v_fmamk_f32 v2, v2, 0x3a2aaaab, v34
	v_fmac_f32_e32 v34, 0x3b000000, v6
	v_mul_f32_e32 v3, 0x4f800000, v2
	v_cmp_gt_f32_e32 vcc, s8, v2
	v_mul_f32_e32 v4, 0x4f800000, v34
	v_cmp_gt_f32_e64 s[0:1], s8, v34
	v_cndmask_b32_e32 v2, v2, v3, vcc
	v_sqrt_f32_e32 v3, v2
	v_cndmask_b32_e64 v4, v34, v4, s[0:1]
	v_sqrt_f32_e32 v5, v4
	v_add_u32_e32 v6, -1, v3
	v_fma_f32 v10, -v6, v3, v2
	v_add_u32_e32 v8, -1, v5
	v_add_u32_e32 v7, 1, v3
	v_fma_f32 v12, -v8, v5, v4
	v_cmp_ge_f32_e64 s[2:3], 0, v10
	v_add_u32_e32 v9, 1, v5
	v_fma_f32 v11, -v7, v3, v2
	v_cndmask_b32_e64 v3, v3, v6, s[2:3]
	v_cmp_ge_f32_e64 s[2:3], 0, v12
	v_fma_f32 v13, -v9, v5, v4
	s_nop 0
	v_cndmask_b32_e64 v5, v5, v8, s[2:3]
	v_cmp_lt_f32_e64 s[2:3], 0, v11
	s_nop 1
	v_cndmask_b32_e64 v3, v3, v7, s[2:3]
	v_cmp_lt_f32_e64 s[2:3], 0, v13
	v_mul_f32_e32 v6, 0x37800000, v3
	v_cndmask_b32_e32 v3, v3, v6, vcc
	v_cndmask_b32_e64 v5, v5, v9, s[2:3]
	v_mul_f32_e32 v7, 0x37800000, v5
	v_cmp_class_f32_e32 vcc, v2, v35
	v_cndmask_b32_e64 v5, v5, v7, s[0:1]
	s_nop 0
	v_cndmask_b32_e32 v2, v3, v2, vcc
	v_cmp_class_f32_e32 vcc, v4, v35
	s_nop 1
	v_cndmask_b32_e32 v3, v5, v4, vcc
	v_div_scale_f32 v4, s[0:1], v2, v2, 1.0
	v_rcp_f32_e32 v6, v4
	v_div_scale_f32 v5, s[0:1], v3, v3, 1.0
	v_rcp_f32_e32 v7, v5
	v_fma_f32 v9, -v4, v6, 1.0
	v_div_scale_f32 v8, vcc, 1.0, v2, 1.0
	v_fmac_f32_e32 v6, v9, v6
	v_fma_f32 v10, -v5, v7, 1.0
	v_mul_f32_e32 v9, v8, v6
	v_fmac_f32_e32 v7, v10, v7
	v_fma_f32 v10, -v4, v9, v8
	v_fmac_f32_e32 v9, v10, v6
	v_fma_f32 v4, -v4, v9, v8
	v_div_fmas_f32 v4, v4, v6, v9
	v_div_fixup_f32 v2, v4, v2, 1.0
	ds_write_b32 v36, v2
	v_div_scale_f32 v2, vcc, 1.0, v3, 1.0
	v_mul_f32_e32 v4, v2, v7
	v_fma_f32 v6, -v5, v4, v2
	v_fmac_f32_e32 v4, v6, v7
	s_mul_i32 s0, s50, 24
	v_fma_f32 v2, -v5, v4, v2
	s_add_i32 s45, s45, s0
	v_div_fmas_f32 v2, v2, v7, v4
	s_cmp_lg_u32 s44, 0
	v_div_fixup_f32 v2, v2, v3, 1.0
	v_add_u32_e32 v3, 0x21800, v178
	s_cselect_b64 s[0:1], -1, 0
	s_cmp_eq_u32 s44, 0
	ds_write_b32 v3, v2
	s_waitcnt lgkmcnt(0)
	s_barrier
	s_cbranch_scc1 .LBB0_712
	s_mul_hi_i32 s2, s45, 0x2aaaaaab
	s_lshr_b32 s3, s2, 31
	s_ashr_i32 s2, s2, 1
	s_add_i32 s16, s2, s3
	s_mul_i32 s2, s16, -12
	s_add_i32 s76, s2, s45
	s_andn2_b64 vcc, exec, s[0:1]
	s_cbranch_vccz .LBB0_713
	s_branch .LBB0_764
